# v81 + MLA loop: next-tile V read base and the five DMA offset increments computed in the gaps of the second step's QK MFMA chain
# speedup vs baseline: 1.0047x; 1.0047x over previous
; #define LAS __attribute__((address_space(3)))
; template <int TAG = 0> DI int fresh_tid(int wv) { int l; asm volatile("v_mbcnt_lo_u32_b32 %0, -1, 0\n\tv_mbcnt_hi_u32_b32 %0, -1, %0 ; site %1" : "=v"(l) : "n"(TAG)); return wv * 64 + l; }
; #define ATT_DMA_K(t) do { const bf16_t* kg_ = Kh + (size_t)(t) * 64 * LDK; LAS unsigned char* sb_ = lds + ((t) & 3) * KBUF; \
;     _Pragma("unroll") for (int i_ = 0; i_ < NKP; ++i_) __builtin_amdgcn_global_load_lds((const unsigned*)(kg_ + kgo[i_]), (LAS unsigned*)(sb_ + (wid + 8 * i_) * 1024), 16, 0, 0); } while (0)
; #define ATT_DMA_V(t, vs) do { const bf16_t* vg_ = Vh + (size_t)(t) * 64 * LDV; LAS unsigned char* sb_ = lds + V_OFF + (vs) * SHM_V; \
;     _Pragma("unroll") for (int i_ = 0; i_ < 2; ++i_) __builtin_amdgcn_global_load_lds((const unsigned*)(vg_ + vgo[i_]), (LAS unsigned*)(sb_ + (2 * wid + i_) * 1024), 16, 0, 0); } while (0)
; template <int DQK, int MODE, int LDQ, int LDK, int LDV> ...
;     ...
;     int tid_ = fresh_tid<100 + MODE>(wv); const int tid = tid_, wid = __builtin_amdgcn_readfirstlane(tid >> 6), lane = tid & 63, r32 = lane & 31, hi = lane >> 5;
;     LAS float* ws = (LAS float*)(lds + WS_OFF) + wid * 64; LAS float* li_l = ws;
;     const LAS float* bt = (const LAS float*)(lds + BT_OFF);
;     float l_reg = 0.f; f32x16 o[4];
; #pragma unroll
;     for (int d = 0; d < 4; ++d)
; #pragma unroll
;         for (int r = 0; r < 16; ++r) o[d][r] = 0.f;
;     int kgo[NKP], vgo[2];
; #pragma unroll
;     for (int i = 0; i < NKP; ++i) { const int L = (wid + 8 * i) * 64 + lane, row = L / CPR, slot = L % CPR, cc = (slot & ~7) | ((slot & 7) ^ ((row >> 1) & 7)); kgo[i] = row * LDK + cc * 8; }
; #pragma unroll
;     for (int i = 0; i < 2; ++i) { const int L = (2 * wid + i) * 64 + lane, st = L >> 5, w5 = L & 31, kk = (st >> 2) * 8 + (w5 >> 2), c = (st & 3) * 32 + (w5 & 3) * 8;
;         const int k = (kk & ~0xC) | ((kk & 4) << 1) | ((kk & 8) >> 1); vgo[i] = k * LDV + c; }
;     ...
;     ATT_DMA_K(0); ATT_DMA_K(1); ATT_DMA_V(0, 0); ATT_DMA_K(2); ATT_DMA_V(1, 1);
.LBB0_1981:
	v_and_b32_e32 v0, 63, v36
	v_lshlrev_b32_e32 v1, 3, v0
	v_lshlrev_b32_e32 v2, 4, v0
	v_lshlrev_b32_e32 v0, 1, v0
	v_and_b32_e32 v0, 32, v0
	s_lshl_b32 s42, s86, 7
	s_andn2_b32 s55, s55, 63
	v_and_b32_e32 v2, 0xc0, v2
	s_mulk_i32 s85, 0x180
	v_and_or_b32 v0, v1, s66, v0
	s_add_i32 s0, 0, 0x18000
	v_add3_u32 v130, v2, s0, v0
	s_add_u32 s0, s54, s85
	s_addc_u32 s1, s53, 0
	s_add_u32 s0, s0, 0x1e048000
	s_addc_u32 s1, s1, 0
	v_lshl_add_u64 v[136:137], v[28:29], 1, s[0:1]
	v_lshl_add_u64 v[138:139], v[30:31], 1, s[0:1]
	v_lshl_add_u64 v[140:141], v[32:33], 1, s[0:1]
	s_add_u32 s0, s4, s84
	s_addc_u32 s1, s5, 0
	s_add_u32 s0, s0, 0x24020000
	s_addc_u32 s1, s1, 0
	s_add_i32 s58, s58, s57
	v_add3_u32 v0, s58, v41, v39
	v_lshl_or_b32 v0, v0, 9, v38
	v_add_u32_e32 v0, v0, v40
	v_add_u32_e32 v2, 64, v0
	v_ashrrev_i32_e32 v3, 31, v2
	v_ashrrev_i32_e32 v1, 31, v0
	v_mov_b32_e32 v173, 0
	v_mul_u32_u24_e32 v159, 0x180, v37
	s_mov_b32 s43, 3
	s_mov_b32 s44, 1
	v_lshl_add_u64 v[142:143], v[2:3], 1, s[0:1]
	v_lshl_add_u64 v[144:145], v[0:1], 1, s[0:1]
	s_mov_b32 s5, 0
	s_mov_b32 s4, 2
	v_mov_b32_e32 v0, 0
	v_mov_b32_e32 v1, v173
	v_mov_b32_e32 v2, v173
	v_mov_b32_e32 v3, v173
	v_mov_b32_e32 v4, v173
	v_mov_b32_e32 v5, v173
	v_mov_b32_e32 v6, v173
	v_mov_b32_e32 v7, v173
	v_mov_b32_e32 v8, v173
	v_mov_b32_e32 v9, v173
	v_mov_b32_e32 v10, v173
	v_mov_b32_e32 v11, v173
	v_mov_b32_e32 v12, v173
	v_mov_b32_e32 v13, v173
	v_mov_b32_e32 v14, v173
	v_mov_b32_e32 v15, v173
	v_mov_b32_e32 v16, 0
	v_mov_b32_e32 v17, v173
	v_mov_b32_e32 v18, v173
	v_mov_b32_e32 v19, v173
	v_mov_b32_e32 v20, v173
	v_mov_b32_e32 v21, v173
	v_mov_b32_e32 v22, v173
	v_mov_b32_e32 v23, v173
	v_mov_b32_e32 v24, v173
	v_mov_b32_e32 v25, v173
	v_mov_b32_e32 v26, v173
	v_mov_b32_e32 v27, v173
	v_mov_b32_e32 v28, v173
	v_mov_b32_e32 v29, v173
	v_mov_b32_e32 v30, v173
	v_mov_b32_e32 v31, v173
	v_mov_b32_e32 v32, 0
	v_mov_b32_e32 v33, v173
	v_mov_b32_e32 v34, v173
	v_mov_b32_e32 v35, v173
	v_mov_b32_e32 v36, v173
	v_mov_b32_e32 v37, v173
	v_mov_b32_e32 v38, v173
	v_mov_b32_e32 v39, v173
	v_mov_b32_e32 v40, v173
	v_mov_b32_e32 v41, v173
	v_mov_b32_e32 v42, v173
	v_mov_b32_e32 v43, v173
	v_mov_b32_e32 v44, v173
	v_mov_b32_e32 v45, v173
	v_mov_b32_e32 v46, v173
	v_mov_b32_e32 v47, v173
	v_mov_b32_e32 v48, 0
	v_mov_b32_e32 v49, v173
	v_mov_b32_e32 v50, v173
	v_mov_b32_e32 v51, v173
	v_mov_b32_e32 v52, v173
	v_mov_b32_e32 v53, v173
	v_mov_b32_e32 v54, v173
	v_mov_b32_e32 v55, v173
	v_mov_b32_e32 v56, v173
	v_mov_b32_e32 v57, v173
	v_mov_b32_e32 v58, v173
	v_mov_b32_e32 v59, v173
	v_mov_b32_e32 v60, v173
	v_mov_b32_e32 v61, v173
	v_mov_b32_e32 v62, v173
	v_mov_b32_e32 v63, v173
	v_lshl_add_u32 v254, s5, 14, v130
	s_cmp_lt_u32 s33, 0x100
	s_cbranch_scc1 .LBB0_1982
	s_waitcnt vmcnt(5)
	s_barrier
.Lhw_mla_b_n1982:
	s_and_b32 s1, s43, 3
	s_mulk_i32 s1, 0x6000
	s_add_i32 s1, s49, s1
	s_setprio 0
	s_mov_b32 m0, s1
	s_mov_b32 s0, s5
	s_mov_b32 s5, s44
	s_mov_b32 s44, s4
	s_lshl_b32 s4, s4, 14
	global_load_lds_dwordx4 v136, s[34:35]
	s_add_i32 m0, s1, 0x2000
	s_add_i32 s4, s52, s4
	global_load_lds_dwordx4 v138, s[34:35]
	s_add_i32 m0, s1, 0x4000
	s_add_i32 s6, s4, 0x400
	global_load_lds_dwordx4 v140, s[34:35]
	s_mov_b32 m0, s4
	s_add_i32 s1, s43, -3
	global_load_lds_dwordx4 v144, s[34:35]
	s_mov_b32 m0, s6
	s_nop 0
	global_load_lds_dwordx4 v142, s[34:35]
	s_and_b32 s1, s1, 3
	s_mulk_i32 s1, 0x6000
	v_add_u32_e32 v246, s1, v158
	v_add_u32_e32 v250, v246, v151
	v_add_u32_e32 v251, v246, v149
	v_add_u32_e32 v252, v246, v148
	v_add_u32_e32 v253, v246, v147
	s_lshl_b32 s1, s0, 14
	ds_read_b128 v[190:193], v250 offset:12416
	ds_read_b128 v[194:197], v251 offset:12416
	ds_read_b128 v[174:177], v250 offset:12288
	ds_read_b128 v[178:181], v251 offset:12288
	ds_read_b128 v[182:185], v252 offset:12288
	ds_read_b128 v[186:189], v253 offset:12288
	ds_read_b64_tr_b16 v[198:199], v254 offset:0
	ds_read_b64_tr_b16 v[200:201], v254 offset:0x800
	ds_read_b64_tr_b16 v[202:203], v254 offset:0x1000
	ds_read_b64_tr_b16 v[204:205], v254 offset:0x1800
	ds_read_b64_tr_b16 v[206:207], v254 offset:0x200
	ds_read_b64_tr_b16 v[208:209], v254 offset:0xa00
	ds_read_b64_tr_b16 v[210:211], v254 offset:0x1200
	ds_read_b64_tr_b16 v[212:213], v254 offset:0x1a00
	ds_read_b64_tr_b16 v[214:215], v254 offset:0x400
	ds_read_b64_tr_b16 v[216:217], v254 offset:0xc00
	ds_read_b64_tr_b16 v[218:219], v254 offset:0x1400
	ds_read_b64_tr_b16 v[220:221], v254 offset:0x1c00
	ds_read_b64_tr_b16 v[222:223], v254 offset:0x600
	ds_read_b64_tr_b16 v[224:225], v254 offset:0xe00
	ds_read_b64_tr_b16 v[226:227], v254 offset:0x1600
	ds_read_b64_tr_b16 v[228:229], v254 offset:0x1e00
	s_setprio 1
	v_exp_f32_e32 v64, v64
	v_exp_f32_e32 v65, v65
	v_exp_f32_e32 v66, v66
	v_exp_f32_e32 v67, v67
	v_exp_f32_e32 v68, v68
	v_exp_f32_e32 v69, v69
	v_add_f32_e32 v230, v65, v64
	v_exp_f32_e32 v70, v70
	v_add_f32_e32 v230, v66, v230
	v_exp_f32_e32 v71, v71
	v_add_f32_e32 v230, v67, v230
	v_exp_f32_e32 v72, v72
	v_add_f32_e32 v230, v68, v230
	v_exp_f32_e32 v73, v73
	v_add_f32_e32 v230, v69, v230
	v_exp_f32_e32 v74, v74
	v_add_f32_e32 v230, v70, v230
	v_exp_f32_e32 v75, v75
	v_add_f32_e32 v230, v71, v230
	v_exp_f32_e32 v76, v76
	v_add_f32_e32 v230, v72, v230
	v_exp_f32_e32 v77, v77
	v_add_f32_e32 v230, v73, v230
	v_exp_f32_e32 v78, v78
	v_add_f32_e32 v230, v74, v230
	v_exp_f32_e32 v79, v79
	v_add_f32_e32 v230, v75, v230
	v_add_f32_e32 v230, v76, v230
	v_add_f32_e32 v230, v77, v230
	v_add_f32_e32 v230, v78, v230
	v_add_f32_e32 v230, v79, v230
	v_add_f32_e32 v173, v173, v230
	v_cvt_pk_bf16_f32 v64, v64, v65
	v_cvt_pk_bf16_f32 v65, v66, v67
	v_cvt_pk_bf16_f32 v66, v68, v69
	v_cvt_pk_bf16_f32 v67, v70, v71
	v_cvt_pk_bf16_f32 v68, v72, v73
	v_cvt_pk_bf16_f32 v69, v74, v75
	v_cvt_pk_bf16_f32 v70, v76, v77
	v_cvt_pk_bf16_f32 v71, v78, v79
	s_waitcnt lgkmcnt(0)
; #define SBAR() __builtin_amdgcn_sched_barrier(0)
; #define ATT_DMA_K(t) do { const bf16_t* kg_ = Kh + (size_t)(t) * 64 * LDK; LAS unsigned char* sb_ = lds + ((t) & 3) * KBUF; \
;     _Pragma("unroll") for (int i_ = 0; i_ < NKP; ++i_) __builtin_amdgcn_global_load_lds((const unsigned*)(kg_ + kgo[i_]), (LAS unsigned*)(sb_ + (wid + 8 * i_) * 1024), 16, 0, 0); } while (0)
; #define ATT_DMA_V(t, vs) do { const bf16_t* vg_ = Vh + (size_t)(t) * 64 * LDV; LAS unsigned char* sb_ = lds + V_OFF + (vs) * SHM_V; \
;     _Pragma("unroll") for (int i_ = 0; i_ < 2; ++i_) __builtin_amdgcn_global_load_lds((const unsigned*)(vg_ + vgo[i_]), (LAS unsigned*)(sb_ + (2 * wid + i_) * 1024), 16, 0, 0); } while (0)
; #define ATT_SEG(t) do { if constexpr (MODE != 0) { if (((t) == tL && tL > 0) || (t) == tR) { const float f_ = (t) == tR ? fR : fL; l_reg *= f_; \
;     _Pragma("unroll") for (int d = 0; d < 4; ++d) _Pragma("unroll") for (int r = 0; r < 16; ++r) o[d][r] *= f_; } } } while (0)
; #define ATT_TOP(N) do { asm volatile("s_waitcnt vmcnt(%0)" :: "n"(N) : "memory"); __builtin_amdgcn_s_barrier(); asm volatile("" ::: "memory"); } while (0)
; DI void expsum(f32x16& p, float& l_reg, bf16x8& pa0, bf16x8& pa1) {
; #pragma unroll
;     for (int r = 0; r < 16; ++r) p[r] = __builtin_amdgcn_exp2f(p[r]);
;     float ps = 0.f;
; #pragma unroll
;     for (int r = 0; r < 16; ++r) ps += p[r];
;     l_reg += ps; asm volatile("" : "+v"(l_reg));
;     ...
;     ATT_PK4(p, 0, pa0); ATT_PK4(p, 8, pa1);
;     ...
; }
; template <int DQK, int MODE, int LDQ, int LDK, int LDV> ...
;     ...
;     f32x16 pA, pB; bf16x8 pa0, pa1;
;     int v0 = 0, v1 = 1, v2 = 2;
;     ATT_TOP(NKP + 2);
;     { bf16x8 kf[NDA]; k_reads<DQK, 0, NDA>(kf, lds, 0, r32, hi); ATT_LGKM0(); qk_mma<0, NDA>(pA, kf, qr);
;       if constexpr (ND0 > NDA) { bf16x8 kg[ND0 - NDA]; k_reads<DQK, NDA, ND0>(kg, lds, 0, r32, hi); ATT_LGKM0(); qk_mma<NDA, ND0>(pA, kg, qr); }
;       ATT_BIAS(pA, 0, 0); }
;     if (wid >= 4) __builtin_amdgcn_s_setprio(1);
;     for (int j = 0; j < NT; ++j) {
;         if (j + 2 < NT) ATT_TOP(NKP + 2); else ATT_TOP(0);
;         if (j + 3 < NT) ATT_DMA_K(j + 3);
;         if (j + 2 < NT) ATT_DMA_V(j + 2, v2);
;         ATT_SEG(j); SBAR();
;         ATT_STEP(pA, pB, 0, v0, true, 1, j);
;         ATT_STEP(pB, pA, 1, v0, (j + 1 < NT), 0, j + 1);
;         { const int t_ = v0; v0 = v1; v1 = v2; v2 = t_; }
;     }
	ds_read_b128 v[230:233], v252 offset:12416
	ds_read_b128 v[234:237], v253 offset:12416
	ds_read_b128 v[238:241], v250 offset:12544
	ds_read_b128 v[242:245], v251 offset:12544
	ds_read_b128 v[246:249], v252 offset:12544
	ds_read_b128 v[250:253], v253 offset:12544
	s_setprio 2
	v_mfma_f32_32x32x16_bf16 v[48:63], v[64:67], v[198:201], v[48:63]
	v_mfma_f32_32x32x16_bf16 v[32:47], v[64:67], v[206:209], v[32:47]
	v_mfma_f32_32x32x16_bf16 v[16:31], v[64:67], v[214:217], v[16:31]
	v_mfma_f32_32x32x16_bf16 v[0:15], v[64:67], v[222:225], v[0:15]
	v_mfma_f32_32x32x16_bf16 v[48:63], v[68:71], v[202:205], v[48:63]
	v_mfma_f32_32x32x16_bf16 v[32:47], v[68:71], v[210:213], v[32:47]
	v_mfma_f32_32x32x16_bf16 v[16:31], v[68:71], v[218:221], v[16:31]
	v_mfma_f32_32x32x16_bf16 v[0:15], v[68:71], v[226:229], v[0:15]
	s_waitcnt lgkmcnt(0)
	v_mfma_f32_32x32x16_bf16 v[64:79], v[174:177], v[80:83], 0
	v_mfma_f32_32x32x16_bf16 v[64:79], v[178:181], v[84:87], v[64:79]
	v_mfma_f32_32x32x16_bf16 v[64:79], v[182:185], v[88:91], v[64:79]
	v_mfma_f32_32x32x16_bf16 v[64:79], v[186:189], v[92:95], v[64:79]
	v_mfma_f32_32x32x16_bf16 v[64:79], v[190:193], v[96:99], v[64:79]
	v_mfma_f32_32x32x16_bf16 v[64:79], v[194:197], v[100:103], v[64:79]
	v_mfma_f32_32x32x16_bf16 v[64:79], v[230:233], v[104:107], v[64:79]
	v_mfma_f32_32x32x16_bf16 v[64:79], v[234:237], v[108:111], v[64:79]
	v_mfma_f32_32x32x16_bf16 v[64:79], v[238:241], v[112:115], v[64:79]
	v_mfma_f32_32x32x16_bf16 v[64:79], v[242:245], v[116:119], v[64:79]
	v_mfma_f32_32x32x16_bf16 v[64:79], v[246:249], v[120:123], v[64:79]
	v_mfma_f32_32x32x16_bf16 v[64:79], v[250:253], v[124:127], v[64:79]
	s_setprio 0
	s_add_i32 s4, s43, -2
	s_and_b32 s4, s4, 3
	s_mulk_i32 s4, 0x6000
	v_add_u32_e32 v246, s4, v158
	v_add_u32_e32 v250, v246, v151
	v_add_u32_e32 v251, v246, v149
	v_add_u32_e32 v252, v246, v148
	v_add_u32_e32 v253, v246, v147
	ds_read_b128 v[190:193], v250 offset:128
	ds_read_b128 v[194:197], v251 offset:128
	ds_read_b128 v[174:177], v250
	ds_read_b128 v[178:181], v251
	ds_read_b128 v[182:185], v252
	ds_read_b128 v[186:189], v253
	ds_read_b64_tr_b16 v[198:199], v254 offset:0x2000
	ds_read_b64_tr_b16 v[200:201], v254 offset:0x2800
	ds_read_b64_tr_b16 v[202:203], v254 offset:0x3000
	ds_read_b64_tr_b16 v[204:205], v254 offset:0x3800
	ds_read_b64_tr_b16 v[206:207], v254 offset:0x2200
	ds_read_b64_tr_b16 v[208:209], v254 offset:0x2a00
	ds_read_b64_tr_b16 v[210:211], v254 offset:0x3200
	ds_read_b64_tr_b16 v[212:213], v254 offset:0x3a00
	ds_read_b64_tr_b16 v[214:215], v254 offset:0x2400
	ds_read_b64_tr_b16 v[216:217], v254 offset:0x2c00
	ds_read_b64_tr_b16 v[218:219], v254 offset:0x3400
	ds_read_b64_tr_b16 v[220:221], v254 offset:0x3c00
	ds_read_b64_tr_b16 v[222:223], v254 offset:0x2600
	ds_read_b64_tr_b16 v[224:225], v254 offset:0x2e00
	ds_read_b64_tr_b16 v[226:227], v254 offset:0x3600
	ds_read_b64_tr_b16 v[228:229], v254 offset:0x3e00
	s_setprio 1
	v_exp_f32_e32 v64, v64
	v_exp_f32_e32 v65, v65
	v_exp_f32_e32 v66, v66
	v_exp_f32_e32 v67, v67
	v_exp_f32_e32 v68, v68
	v_exp_f32_e32 v69, v69
	v_add_f32_e32 v230, v65, v64
	v_exp_f32_e32 v70, v70
	v_add_f32_e32 v230, v66, v230
	v_exp_f32_e32 v71, v71
	v_add_f32_e32 v230, v67, v230
	v_exp_f32_e32 v72, v72
	v_add_f32_e32 v230, v68, v230
	v_exp_f32_e32 v73, v73
	v_add_f32_e32 v230, v69, v230
	v_exp_f32_e32 v74, v74
	v_add_f32_e32 v230, v70, v230
	v_exp_f32_e32 v75, v75
	v_add_f32_e32 v230, v71, v230
	v_exp_f32_e32 v76, v76
	v_add_f32_e32 v230, v72, v230
	v_exp_f32_e32 v77, v77
	v_add_f32_e32 v230, v73, v230
	v_exp_f32_e32 v78, v78
	v_add_f32_e32 v230, v74, v230
	v_exp_f32_e32 v79, v79
	v_add_f32_e32 v230, v75, v230
	v_add_f32_e32 v230, v76, v230
	v_add_f32_e32 v230, v77, v230
	v_add_f32_e32 v230, v78, v230
	v_add_f32_e32 v230, v79, v230
	v_add_f32_e32 v173, v173, v230
	v_cvt_pk_bf16_f32 v64, v64, v65
	v_cvt_pk_bf16_f32 v65, v66, v67
	v_cvt_pk_bf16_f32 v66, v68, v69
	v_cvt_pk_bf16_f32 v67, v70, v71
	v_cvt_pk_bf16_f32 v68, v72, v73
	v_cvt_pk_bf16_f32 v69, v74, v75
	v_cvt_pk_bf16_f32 v70, v76, v77
	v_cvt_pk_bf16_f32 v71, v78, v79
	s_waitcnt lgkmcnt(0)
	ds_read_b128 v[230:233], v252 offset:128
	ds_read_b128 v[234:237], v253 offset:128
	ds_read_b128 v[238:241], v250 offset:256
	ds_read_b128 v[242:245], v251 offset:256
	ds_read_b128 v[246:249], v252 offset:256
	ds_read_b128 v[250:253], v253 offset:256
	s_setprio 2
	s_waitcnt vmcnt(5)
	s_barrier
	v_mfma_f32_32x32x16_bf16 v[48:63], v[64:67], v[198:201], v[48:63]
	v_mfma_f32_32x32x16_bf16 v[32:47], v[64:67], v[206:209], v[32:47]
	v_mfma_f32_32x32x16_bf16 v[16:31], v[64:67], v[214:217], v[16:31]
	v_mfma_f32_32x32x16_bf16 v[0:15], v[64:67], v[222:225], v[0:15]
	v_mfma_f32_32x32x16_bf16 v[48:63], v[68:71], v[202:205], v[48:63]
	v_mfma_f32_32x32x16_bf16 v[32:47], v[68:71], v[210:213], v[32:47]
	v_mfma_f32_32x32x16_bf16 v[16:31], v[68:71], v[218:221], v[16:31]
	v_mfma_f32_32x32x16_bf16 v[0:15], v[68:71], v[226:229], v[0:15]
	s_waitcnt lgkmcnt(0)
	v_mfma_f32_32x32x16_bf16 v[64:79], v[174:177], v[80:83], 0
	v_lshl_add_u32 v254, s5, 14, v130
	v_mfma_f32_32x32x16_bf16 v[64:79], v[178:181], v[84:87], v[64:79]
	v_add_u32_e32 v136, s36, v136
	v_mfma_f32_32x32x16_bf16 v[64:79], v[182:185], v[88:91], v[64:79]
	v_add_u32_e32 v138, s36, v138
	v_mfma_f32_32x32x16_bf16 v[64:79], v[186:189], v[92:95], v[64:79]
	v_add_u32_e32 v140, s36, v140
	v_mfma_f32_32x32x16_bf16 v[64:79], v[190:193], v[96:99], v[64:79]
	v_add_u32_e32 v142, s38, v142
	v_mfma_f32_32x32x16_bf16 v[64:79], v[194:197], v[100:103], v[64:79]
	v_add_u32_e32 v144, s38, v144
	v_mfma_f32_32x32x16_bf16 v[64:79], v[230:233], v[104:107], v[64:79]
	v_mfma_f32_32x32x16_bf16 v[64:79], v[234:237], v[108:111], v[64:79]
	v_mfma_f32_32x32x16_bf16 v[64:79], v[238:241], v[112:115], v[64:79]
	v_mfma_f32_32x32x16_bf16 v[64:79], v[242:245], v[116:119], v[64:79]
	v_mfma_f32_32x32x16_bf16 v[64:79], v[246:249], v[120:123], v[64:79]
	v_mfma_f32_32x32x16_bf16 v[64:79], v[250:253], v[124:127], v[64:79]
	s_add_i32 s43, s43, 1
	s_cmp_eq_u32 s43, 64
	s_mov_b32 s4, s0
	s_cbranch_scc0 .Lhw_mla_b_n1982
	s_branch .Lhw_mla_exit
; DI float bf2f(unsigned short h) { return __uint_as_float((unsigned)h << 16); }
; DI unsigned cvtpk(float lo, float hi) { unsigned r; asm volatile("v_cvt_pk_bf16_f32 %0, %1, %2" : "=v"(r) : "v"(lo), "v"(hi)); return r; }
; DI float swap_sum(float v) { auto rr = __builtin_amdgcn_permlane32_swap(__float_as_uint(v), __float_as_uint(v), false, false); return __uint_as_float(rr[0]) + __uint_as_float(rr[1]); }
; DI void expsum(f32x16& p, float& l_reg, bf16x8& pa0, bf16x8& pa1) {
; #pragma unroll
;     for (int r = 0; r < 16; ++r) p[r] = __builtin_amdgcn_exp2f(p[r]);
;     float ps = 0.f;
; #pragma unroll
;     for (int r = 0; r < 16; ++r) ps += p[r];
;     l_reg += ps; asm volatile("" : "+v"(l_reg));
;     ...
;     ATT_PK4(p, 0, pa0); ATT_PK4(p, 8, pa1);
;     ...
; }
; template <int DQK, int MODE, int LDQ, int LDK, int LDV> ...
;     ...
;     ATT_DMA_K(0); ATT_DMA_K(1); ATT_DMA_V(0, 0); ATT_DMA_K(2); ATT_DMA_V(1, 1);
;     bf16x8 qr[ND0];
;     { const bf16_t* Qw = Qb + (size_t)(wid * 32 + r32) * LDQ + hi * 8;
; #pragma unroll
;       for (int d0 = 0; d0 < ND0; ++d0) qr[d0] = *(const bf16x8*)(Qw + d0 * 16);
;       if constexpr (MODE == 0) {
;           float ss = 0.f;
; #pragma unroll
;           for (int d0 = 0; d0 < ND0; ++d0)
; #pragma unroll
;               for (int j = 0; j < 8; ++j) { const float f = bf2f((unsigned short)qr[d0][j]); ss += f * f; }
;           ss = swap_sum(ss);
;           const float rstd = rsqrtf(ss * (1.f / DQK) + EPS) * C;
; #pragma unroll
;           for (int d0 = 0; d0 < ND0; ++d0) { const float* g = gq + d0 * 16 + hi * 8;
;               { float f[8]; _Pragma("unroll") for (int j = 0; j < 8; ++j) f[j] = bf2f((unsigned short)qr[d0][j]) * rstd * g[j];
;                 u32x4 w = {cvtpk(f[0], f[1]), cvtpk(f[2], f[3]), cvtpk(f[4], f[5]), cvtpk(f[6], f[7])}; qr[d0] = __builtin_bit_cast(bf16x8, w); asm volatile("" ::: "memory"); } }
;       } }
;     const int qlo = q0 + wid * 32, qpos = qlo + r32;
;     const int tL = MODE == 0 ? 0 : (qlo >= 191 ? (qlo - 127) >> 6 : 0), tR = MODE == 0 ? NT : min(NT, (qlo + 222) >> 6);
;     float fL = 1.f, fR = 1.f; if constexpr (MODE != 0) { fL = __builtin_amdgcn_exp2f(bt[0]); fR = __builtin_amdgcn_exp2f(-bt[448]); }
;     ...
;     const int vbase = (int)(unsigned)(size_t)lds + V_OFF + v_rd_base(lane);
;     ...
;     constexpr int NDA = ND0 > 6 ? 6 : ND0;
.LBB0_1982:
	s_and_b32 s1, s43, 3
	s_mulk_i32 s1, 0x6000
	s_add_i32 s1, s49, s1
	s_waitcnt vmcnt(5)
	s_barrier
	s_setprio 0
	s_mov_b32 m0, s1
	s_mov_b32 s0, s5
	s_mov_b32 s5, s44
	s_mov_b32 s44, s4
	s_lshl_b32 s4, s4, 14
	global_load_lds_dwordx4 v136, s[34:35]
	s_add_i32 m0, s1, 0x2000
	s_add_i32 s4, s52, s4
	global_load_lds_dwordx4 v138, s[34:35]
	s_add_i32 m0, s1, 0x4000
	s_add_i32 s6, s4, 0x400
	global_load_lds_dwordx4 v140, s[34:35]
	s_mov_b32 m0, s4
	s_add_i32 s1, s43, -3
	global_load_lds_dwordx4 v144, s[34:35]
	s_mov_b32 m0, s6
	s_nop 0
	global_load_lds_dwordx4 v142, s[34:35]
	s_and_b32 s1, s1, 3
	s_mulk_i32 s1, 0x6000
	v_add_u32_e32 v246, s1, v158
	v_add_u32_e32 v250, v246, v151
	v_add_u32_e32 v251, v246, v149
	v_add_u32_e32 v252, v246, v148
	v_add_u32_e32 v253, v246, v147
	s_lshl_b32 s1, s0, 14
	ds_read_b128 v[190:193], v250 offset:12416
	ds_read_b128 v[194:197], v251 offset:12416
	ds_read_b128 v[174:177], v250 offset:12288
	ds_read_b128 v[178:181], v251 offset:12288
	ds_read_b128 v[182:185], v252 offset:12288
	ds_read_b128 v[186:189], v253 offset:12288
	ds_read_b64_tr_b16 v[198:199], v254 offset:0
	ds_read_b64_tr_b16 v[200:201], v254 offset:0x800
	ds_read_b64_tr_b16 v[202:203], v254 offset:0x1000
	ds_read_b64_tr_b16 v[204:205], v254 offset:0x1800
	ds_read_b64_tr_b16 v[206:207], v254 offset:0x200
	ds_read_b64_tr_b16 v[208:209], v254 offset:0xa00
	ds_read_b64_tr_b16 v[210:211], v254 offset:0x1200
	ds_read_b64_tr_b16 v[212:213], v254 offset:0x1a00
	ds_read_b64_tr_b16 v[214:215], v254 offset:0x400
	ds_read_b64_tr_b16 v[216:217], v254 offset:0xc00
	ds_read_b64_tr_b16 v[218:219], v254 offset:0x1400
	ds_read_b64_tr_b16 v[220:221], v254 offset:0x1c00
	ds_read_b64_tr_b16 v[222:223], v254 offset:0x600
	ds_read_b64_tr_b16 v[224:225], v254 offset:0xe00
	ds_read_b64_tr_b16 v[226:227], v254 offset:0x1600
	ds_read_b64_tr_b16 v[228:229], v254 offset:0x1e00
	s_setprio 1
	v_exp_f32_e32 v64, v64
	v_exp_f32_e32 v65, v65
	v_exp_f32_e32 v66, v66
	v_exp_f32_e32 v67, v67
	v_exp_f32_e32 v68, v68
	v_exp_f32_e32 v69, v69
	v_add_f32_e32 v230, v65, v64
	v_exp_f32_e32 v70, v70
	v_add_f32_e32 v230, v66, v230
	v_exp_f32_e32 v71, v71
	v_add_f32_e32 v230, v67, v230
	v_exp_f32_e32 v72, v72
	v_add_f32_e32 v230, v68, v230
	v_exp_f32_e32 v73, v73
	v_add_f32_e32 v230, v69, v230
	v_exp_f32_e32 v74, v74
	v_add_f32_e32 v230, v70, v230
	v_exp_f32_e32 v75, v75
	v_add_f32_e32 v230, v71, v230
	v_exp_f32_e32 v76, v76
	v_add_f32_e32 v230, v72, v230
	v_exp_f32_e32 v77, v77
	v_add_f32_e32 v230, v73, v230
	v_exp_f32_e32 v78, v78
	v_add_f32_e32 v230, v74, v230
	v_exp_f32_e32 v79, v79
	v_add_f32_e32 v230, v75, v230
	v_add_f32_e32 v230, v76, v230
	v_add_f32_e32 v230, v77, v230
	v_add_f32_e32 v230, v78, v230
	v_add_f32_e32 v230, v79, v230
	v_add_f32_e32 v173, v173, v230
	v_cvt_pk_bf16_f32 v64, v64, v65
	v_cvt_pk_bf16_f32 v65, v66, v67
	v_cvt_pk_bf16_f32 v66, v68, v69
	v_cvt_pk_bf16_f32 v67, v70, v71
	v_cvt_pk_bf16_f32 v68, v72, v73
	v_cvt_pk_bf16_f32 v69, v74, v75
	v_cvt_pk_bf16_f32 v70, v76, v77
	v_cvt_pk_bf16_f32 v71, v78, v79
	s_waitcnt lgkmcnt(0)
	ds_read_b128 v[230:233], v252 offset:12416
	ds_read_b128 v[234:237], v253 offset:12416
	ds_read_b128 v[238:241], v250 offset:12544
	ds_read_b128 v[242:245], v251 offset:12544
	ds_read_b128 v[246:249], v252 offset:12544
	ds_read_b128 v[250:253], v253 offset:12544
	s_setprio 2
	v_mfma_f32_32x32x16_bf16 v[48:63], v[64:67], v[198:201], v[48:63]
	v_mfma_f32_32x32x16_bf16 v[32:47], v[64:67], v[206:209], v[32:47]
	v_mfma_f32_32x32x16_bf16 v[16:31], v[64:67], v[214:217], v[16:31]
	v_mfma_f32_32x32x16_bf16 v[0:15], v[64:67], v[222:225], v[0:15]
	v_mfma_f32_32x32x16_bf16 v[48:63], v[68:71], v[202:205], v[48:63]
	v_mfma_f32_32x32x16_bf16 v[32:47], v[68:71], v[210:213], v[32:47]
	v_mfma_f32_32x32x16_bf16 v[16:31], v[68:71], v[218:221], v[16:31]
	v_mfma_f32_32x32x16_bf16 v[0:15], v[68:71], v[226:229], v[0:15]
	s_waitcnt lgkmcnt(0)
; #define SBAR() __builtin_amdgcn_sched_barrier(0)
; #define ATT_DMA_K(t) do { const bf16_t* kg_ = Kh + (size_t)(t) * 64 * LDK; LAS unsigned char* sb_ = lds + ((t) & 3) * KBUF; \
;     _Pragma("unroll") for (int i_ = 0; i_ < NKP; ++i_) __builtin_amdgcn_global_load_lds((const unsigned*)(kg_ + kgo[i_]), (LAS unsigned*)(sb_ + (wid + 8 * i_) * 1024), 16, 0, 0); } while (0)
; #define ATT_DMA_V(t, vs) do { const bf16_t* vg_ = Vh + (size_t)(t) * 64 * LDV; LAS unsigned char* sb_ = lds + V_OFF + (vs) * SHM_V; \
;     _Pragma("unroll") for (int i_ = 0; i_ < 2; ++i_) __builtin_amdgcn_global_load_lds((const unsigned*)(vg_ + vgo[i_]), (LAS unsigned*)(sb_ + (2 * wid + i_) * 1024), 16, 0, 0); } while (0)
; #define ATT_SEG(t) do { if constexpr (MODE != 0) { if (((t) == tL && tL > 0) || (t) == tR) { const float f_ = (t) == tR ? fR : fL; l_reg *= f_; \
;     _Pragma("unroll") for (int d = 0; d < 4; ++d) _Pragma("unroll") for (int r = 0; r < 16; ++r) o[d][r] *= f_; } } } while (0)
; #define ATT_TOP(N) do { asm volatile("s_waitcnt vmcnt(%0)" :: "n"(N) : "memory"); __builtin_amdgcn_s_barrier(); asm volatile("" ::: "memory"); } while (0)
; DI void expsum(f32x16& p, float& l_reg, bf16x8& pa0, bf16x8& pa1) {
; #pragma unroll
;     for (int r = 0; r < 16; ++r) p[r] = __builtin_amdgcn_exp2f(p[r]);
;     float ps = 0.f;
; #pragma unroll
;     for (int r = 0; r < 16; ++r) ps += p[r];
;     l_reg += ps; asm volatile("" : "+v"(l_reg));
;     ...
;     ATT_PK4(p, 0, pa0); ATT_PK4(p, 8, pa1);
;     ...
; }
; template <int DQK, int MODE, int LDQ, int LDK, int LDV> ...
;     ...
;     f32x16 pA, pB; bf16x8 pa0, pa1;
;     int v0 = 0, v1 = 1, v2 = 2;
;     ATT_TOP(NKP + 2);
;     { bf16x8 kf[NDA]; k_reads<DQK, 0, NDA>(kf, lds, 0, r32, hi); ATT_LGKM0(); qk_mma<0, NDA>(pA, kf, qr);
;       if constexpr (ND0 > NDA) { bf16x8 kg[ND0 - NDA]; k_reads<DQK, NDA, ND0>(kg, lds, 0, r32, hi); ATT_LGKM0(); qk_mma<NDA, ND0>(pA, kg, qr); }
;       ATT_BIAS(pA, 0, 0); }
;     if (wid >= 4) __builtin_amdgcn_s_setprio(1);
;     for (int j = 0; j < NT; ++j) {
;         if (j + 2 < NT) ATT_TOP(NKP + 2); else ATT_TOP(0);
;         if (j + 3 < NT) ATT_DMA_K(j + 3);
;         if (j + 2 < NT) ATT_DMA_V(j + 2, v2);
;         ATT_SEG(j); SBAR();
;         ATT_STEP(pA, pB, 0, v0, true, 1, j);
;         ATT_STEP(pB, pA, 1, v0, (j + 1 < NT), 0, j + 1);
;         { const int t_ = v0; v0 = v1; v1 = v2; v2 = t_; }
;     }
	v_mfma_f32_32x32x16_bf16 v[64:79], v[174:177], v[80:83], 0
	v_mfma_f32_32x32x16_bf16 v[64:79], v[178:181], v[84:87], v[64:79]
	v_mfma_f32_32x32x16_bf16 v[64:79], v[182:185], v[88:91], v[64:79]
	v_mfma_f32_32x32x16_bf16 v[64:79], v[186:189], v[92:95], v[64:79]
	v_mfma_f32_32x32x16_bf16 v[64:79], v[190:193], v[96:99], v[64:79]
	v_mfma_f32_32x32x16_bf16 v[64:79], v[194:197], v[100:103], v[64:79]
	v_mfma_f32_32x32x16_bf16 v[64:79], v[230:233], v[104:107], v[64:79]
	v_mfma_f32_32x32x16_bf16 v[64:79], v[234:237], v[108:111], v[64:79]
	v_mfma_f32_32x32x16_bf16 v[64:79], v[238:241], v[112:115], v[64:79]
	v_mfma_f32_32x32x16_bf16 v[64:79], v[242:245], v[116:119], v[64:79]
	v_mfma_f32_32x32x16_bf16 v[64:79], v[246:249], v[120:123], v[64:79]
	v_mfma_f32_32x32x16_bf16 v[64:79], v[250:253], v[124:127], v[64:79]
	s_setprio 0
	s_add_i32 s4, s43, -2
	s_and_b32 s4, s4, 3
	s_mulk_i32 s4, 0x6000
	v_add_u32_e32 v246, s4, v158
	v_add_u32_e32 v250, v246, v151
	v_add_u32_e32 v251, v246, v149
	v_add_u32_e32 v252, v246, v148
	v_add_u32_e32 v253, v246, v147
	ds_read_b128 v[190:193], v250 offset:128
	ds_read_b128 v[194:197], v251 offset:128
	ds_read_b128 v[174:177], v250
	ds_read_b128 v[178:181], v251
	ds_read_b128 v[182:185], v252
	ds_read_b128 v[186:189], v253
	ds_read_b64_tr_b16 v[198:199], v254 offset:0x2000
	ds_read_b64_tr_b16 v[200:201], v254 offset:0x2800
	ds_read_b64_tr_b16 v[202:203], v254 offset:0x3000
	ds_read_b64_tr_b16 v[204:205], v254 offset:0x3800
	ds_read_b64_tr_b16 v[206:207], v254 offset:0x2200
	ds_read_b64_tr_b16 v[208:209], v254 offset:0x2a00
	ds_read_b64_tr_b16 v[210:211], v254 offset:0x3200
	ds_read_b64_tr_b16 v[212:213], v254 offset:0x3a00
	ds_read_b64_tr_b16 v[214:215], v254 offset:0x2400
	ds_read_b64_tr_b16 v[216:217], v254 offset:0x2c00
	ds_read_b64_tr_b16 v[218:219], v254 offset:0x3400
	ds_read_b64_tr_b16 v[220:221], v254 offset:0x3c00
	ds_read_b64_tr_b16 v[222:223], v254 offset:0x2600
	ds_read_b64_tr_b16 v[224:225], v254 offset:0x2e00
	ds_read_b64_tr_b16 v[226:227], v254 offset:0x3600
	ds_read_b64_tr_b16 v[228:229], v254 offset:0x3e00
	s_setprio 1
	v_exp_f32_e32 v64, v64
	v_exp_f32_e32 v65, v65
	v_exp_f32_e32 v66, v66
	v_exp_f32_e32 v67, v67
	v_exp_f32_e32 v68, v68
	v_exp_f32_e32 v69, v69
	v_add_f32_e32 v230, v65, v64
	v_exp_f32_e32 v70, v70
	v_add_f32_e32 v230, v66, v230
	v_exp_f32_e32 v71, v71
	v_add_f32_e32 v230, v67, v230
	v_exp_f32_e32 v72, v72
	v_add_f32_e32 v230, v68, v230
	v_exp_f32_e32 v73, v73
	v_add_f32_e32 v230, v69, v230
	v_exp_f32_e32 v74, v74
	v_add_f32_e32 v230, v70, v230
	v_exp_f32_e32 v75, v75
	v_add_f32_e32 v230, v71, v230
	v_exp_f32_e32 v76, v76
	v_add_f32_e32 v230, v72, v230
	v_exp_f32_e32 v77, v77
	v_add_f32_e32 v230, v73, v230
	v_exp_f32_e32 v78, v78
	v_add_f32_e32 v230, v74, v230
	v_exp_f32_e32 v79, v79
	v_add_f32_e32 v230, v75, v230
	v_add_f32_e32 v230, v76, v230
	v_add_f32_e32 v230, v77, v230
	v_add_f32_e32 v230, v78, v230
	v_add_f32_e32 v230, v79, v230
	v_add_f32_e32 v173, v173, v230
	v_cvt_pk_bf16_f32 v64, v64, v65
	v_cvt_pk_bf16_f32 v65, v66, v67
	v_cvt_pk_bf16_f32 v66, v68, v69
	v_cvt_pk_bf16_f32 v67, v70, v71
	v_cvt_pk_bf16_f32 v68, v72, v73
	v_cvt_pk_bf16_f32 v69, v74, v75
	v_cvt_pk_bf16_f32 v70, v76, v77
	v_cvt_pk_bf16_f32 v71, v78, v79
	s_waitcnt lgkmcnt(0)
	ds_read_b128 v[230:233], v252 offset:128
	ds_read_b128 v[234:237], v253 offset:128
	ds_read_b128 v[238:241], v250 offset:256
	ds_read_b128 v[242:245], v251 offset:256
	ds_read_b128 v[246:249], v252 offset:256
	ds_read_b128 v[250:253], v253 offset:256
	s_setprio 2
	v_mfma_f32_32x32x16_bf16 v[48:63], v[64:67], v[198:201], v[48:63]
	v_mfma_f32_32x32x16_bf16 v[32:47], v[64:67], v[206:209], v[32:47]
	v_mfma_f32_32x32x16_bf16 v[16:31], v[64:67], v[214:217], v[16:31]
	v_mfma_f32_32x32x16_bf16 v[0:15], v[64:67], v[222:225], v[0:15]
	v_mfma_f32_32x32x16_bf16 v[48:63], v[68:71], v[202:205], v[48:63]
	v_mfma_f32_32x32x16_bf16 v[32:47], v[68:71], v[210:213], v[32:47]
	v_mfma_f32_32x32x16_bf16 v[16:31], v[68:71], v[218:221], v[16:31]
	v_mfma_f32_32x32x16_bf16 v[0:15], v[68:71], v[226:229], v[0:15]
	s_waitcnt lgkmcnt(0)
	v_mfma_f32_32x32x16_bf16 v[64:79], v[174:177], v[80:83], 0
	v_lshl_add_u32 v254, s5, 14, v130
	v_mfma_f32_32x32x16_bf16 v[64:79], v[178:181], v[84:87], v[64:79]
	v_add_u32_e32 v136, s36, v136
	v_mfma_f32_32x32x16_bf16 v[64:79], v[182:185], v[88:91], v[64:79]
	v_add_u32_e32 v138, s36, v138
	v_mfma_f32_32x32x16_bf16 v[64:79], v[186:189], v[92:95], v[64:79]
	v_add_u32_e32 v140, s36, v140
	v_mfma_f32_32x32x16_bf16 v[64:79], v[190:193], v[96:99], v[64:79]
	v_add_u32_e32 v142, s38, v142
	v_mfma_f32_32x32x16_bf16 v[64:79], v[194:197], v[100:103], v[64:79]
	v_add_u32_e32 v144, s38, v144
	v_mfma_f32_32x32x16_bf16 v[64:79], v[230:233], v[104:107], v[64:79]
	v_mfma_f32_32x32x16_bf16 v[64:79], v[234:237], v[108:111], v[64:79]
	v_mfma_f32_32x32x16_bf16 v[64:79], v[238:241], v[112:115], v[64:79]
	v_mfma_f32_32x32x16_bf16 v[64:79], v[242:245], v[116:119], v[64:79]
	v_mfma_f32_32x32x16_bf16 v[64:79], v[246:249], v[120:123], v[64:79]
	v_mfma_f32_32x32x16_bf16 v[64:79], v[250:253], v[124:127], v[64:79]
	s_add_i32 s43, s43, 1
	s_cmp_eq_u32 s43, 64
	s_mov_b32 s4, s0
	s_cbranch_scc0 .LBB0_1982
